# MoBA K/V fragment LDS prefetch 8 deep with counted lgkmcnt; prologue transpose item: 8 row loads + gains issued together (counted vmcnt)
# speedup vs baseline: 1.0089x; 1.0089x over previous
; #define LAS __attribute__((address_space(3)))
; #define LDS_WAIT() asm volatile("s_waitcnt lgkmcnt(0)" ::: "memory")
; __device__ __forceinline__ unsigned pk2(float lo, float hi) { return f2bf(lo) | (f2bf(hi) << 16); }
; __device__ __forceinline__ void transpose_item(const Job& jb, LAS float* scr, int item, int lane) {
;     ...
;     for (int i = 0; i < 8; ++i) { const int kk = 8 * i + (lane >> 3), c4 = 4 * (lane & 7); const float g = jb.gain ? jb.gain[k0 + kk] : 1.0f;
;         const f32x4 v = *(const f32x4*)(jb.src + (size_t)(k0 + kk) * N + n0 + c4); LAS float* d = scr + kk * 33 + c4;
;         d[0] = v.x * g; d[1] = v.y * g; d[2] = v.z * g; d[3] = v.w * g; }
;     LDS_WAIT(); asm volatile("" ::: "memory");
;     const int c = lane & 7;
; #pragma unroll
;     for (int j = 0; j < 4; ++j) { const int n = (lane >> 3) + 8 * j; const LAS float* s = scr + (8 * c) * 33 + n;
;         v4u o; o.x = pk2(s[0 * 33], s[1 * 33]); o.y = pk2(s[2 * 33], s[3 * 33]); o.z = pk2(s[4 * 33], s[5 * 33]); o.w = pk2(s[6 * 33], s[7 * 33]);
;         *(v4u*)(jb.dst + (size_t)(r0 + n) * K + k0 + 8 * c) = o; }
;     LDS_WAIT(); asm volatile("" ::: "memory");
.LBB0_7:
	v_add_u32_e32 v8, s15, v2
	v_add_u32_e32 v12, s15, v13
	v_ashrrev_i32_e32 v33, 31, v8
	v_mad_u64_u32 v[8:9], s[10:11], v8, s14, 0
	v_mad_u64_u32 v[14:15], s[10:11], v12, s14, 0
	v_ashrrev_i32_e32 v38, 31, v12
	v_mov_b32_e32 v12, v9
	v_mov_b32_e32 v32, v15
	v_mad_u64_u32 v[34:35], s[10:11], v33, s14, v[12:13]
	v_mad_u64_u32 v[32:33], s[10:11], v38, s14, v[32:33]
	v_mov_b32_e32 v9, v34
	v_mov_b32_e32 v15, v32
	s_lshl_b64 s[0:1], s[12:13], 1
	v_lshl_add_u64 v[8:9], v[8:9], 1, s[8:9]
	v_lshl_add_u64 v[14:15], v[14:15], 1, s[8:9]
	v_lshl_add_u64 v[8:9], v[8:9], 0, s[0:1]
	v_lshl_add_u64 v[14:15], v[14:15], 0, s[0:1]
	v_lshl_add_u64 v[8:9], v[8:9], 0, v[4:5]
	v_lshl_add_u64 v[14:15], v[14:15], 0, v[4:5]
	s_add_i32 s97, s97, s80
	s_cmpk_gt_i32 s97, 0x567f
	s_waitcnt lgkmcnt(0)
	ds_read2_b32 v[28:29], v22 offset0:33 offset1:41
	ds_read2_b32 v[30:31], v22 offset1:8
	ds_read2_b32 v[32:33], v22 offset0:66 offset1:74
	ds_read2_b32 v[34:35], v22 offset0:99 offset1:107
	ds_read2_b32 v[36:37], v22 offset0:132 offset1:140
	ds_read2_b32 v[38:39], v22 offset0:165 offset1:173
	ds_read2_b32 v[40:41], v22 offset0:198 offset1:206
	ds_read2_b32 v[42:43], v22 offset0:231 offset1:239
	ds_read2_b32 v[44:45], v22 offset0:16 offset1:24
	ds_read2_b32 v[46:47], v22 offset0:49 offset1:57
	s_waitcnt lgkmcnt(8)
	v_bfe_u32 v10, v30, 16, 1
	v_bfe_u32 v12, v28, 16, 1
	s_waitcnt lgkmcnt(7)
	v_bfe_u32 v48, v32, 16, 1
	s_waitcnt lgkmcnt(5)
	v_bfe_u32 v50, v36, 16, 1
	s_waitcnt lgkmcnt(3)
	v_bfe_u32 v52, v40, 16, 1
	v_bfe_u32 v49, v34, 16, 1
	v_bfe_u32 v51, v38, 16, 1
	s_waitcnt lgkmcnt(2)
	v_bfe_u32 v53, v42, 16, 1
	v_bfe_u32 v54, v31, 16, 1
	v_bfe_u32 v55, v29, 16, 1
	v_bfe_u32 v56, v33, 16, 1
	v_bfe_u32 v57, v35, 16, 1
	v_bfe_u32 v58, v37, 16, 1
	v_bfe_u32 v59, v39, 16, 1
	v_bfe_u32 v60, v41, 16, 1
	v_add3_u32 v10, v30, v10, s5
	v_add3_u32 v12, v28, v12, s5
	v_add3_u32 v28, v32, v48, s5
	v_add3_u32 v32, v36, v50, s5
	v_add3_u32 v36, v40, v52, s5
	v_bfe_u32 v61, v43, 16, 1
	v_add3_u32 v30, v34, v49, s5
	v_add3_u32 v34, v38, v51, s5
	v_add3_u32 v38, v42, v53, s5
	v_add3_u32 v31, v31, v54, s5
	v_add3_u32 v40, v29, v55, s5
	v_add3_u32 v29, v33, v56, s5
	v_add3_u32 v33, v35, v57, s5
	v_add3_u32 v35, v37, v58, s5
	v_add3_u32 v37, v39, v59, s5
	v_add3_u32 v39, v41, v60, s5
	v_lshrrev_b32_e32 v10, 16, v10
	v_lshrrev_b32_e32 v42, 16, v28
	v_lshrrev_b32_e32 v32, 16, v32
	v_lshrrev_b32_e32 v36, 16, v36
	s_waitcnt lgkmcnt(1)
	v_bfe_u32 v62, v44, 16, 1
	v_add3_u32 v41, v43, v61, s5
	v_lshrrev_b32_e32 v43, 16, v31
	v_lshrrev_b32_e32 v48, 16, v29
	v_lshrrev_b32_e32 v35, 16, v35
	v_lshrrev_b32_e32 v39, 16, v39
	v_and_or_b32 v28, v12, s35, v10
	v_and_or_b32 v29, v30, s35, v42
	v_and_or_b32 v30, v34, s35, v32
	v_and_or_b32 v31, v38, s35, v36
	v_and_or_b32 v32, v40, s35, v43
	v_and_or_b32 v33, v33, s35, v48
	v_and_or_b32 v34, v37, s35, v35
	v_and_or_b32 v35, v41, s35, v39
	global_store_dwordx4 v[8:9], v[28:31], off
	global_store_dwordx4 v[14:15], v[32:35], off
	v_add3_u32 v8, v44, v62, s5
	v_lshrrev_b32_e32 v10, 16, v8
	ds_read2_b32 v[8:9], v22 offset0:82 offset1:90
	ds_read2_b32 v[14:15], v22 offset0:115 offset1:123
	s_waitcnt lgkmcnt(2)
	v_bfe_u32 v12, v46, 16, 1
	ds_read2_b32 v[32:33], v22 offset0:148 offset1:156
	v_add3_u32 v12, v46, v12, s5
	ds_read2_b32 v[34:35], v22 offset0:181 offset1:189
	v_and_or_b32 v28, v12, s35, v10
	s_waitcnt lgkmcnt(3)
	v_bfe_u32 v10, v8, 16, 1
	v_add3_u32 v8, v8, v10, s5
	s_waitcnt lgkmcnt(2)
	v_bfe_u32 v10, v14, 16, 1
	ds_read2_b32 v[36:37], v22 offset0:214 offset1:222
	v_lshrrev_b32_e32 v8, 16, v8
	v_add3_u32 v10, v14, v10, s5
	ds_read2_b32 v[38:39], v22 offset0:247 offset1:255
	v_and_or_b32 v29, v10, s35, v8
	s_waitcnt lgkmcnt(3)
	v_bfe_u32 v8, v32, 16, 1
	v_add3_u32 v8, v32, v8, s5
	s_waitcnt lgkmcnt(2)
	v_bfe_u32 v10, v34, 16, 1
	v_lshrrev_b32_e32 v8, 16, v8
	v_add3_u32 v10, v34, v10, s5
	v_and_or_b32 v30, v10, s35, v8
	s_waitcnt lgkmcnt(1)
	v_bfe_u32 v8, v36, 16, 1
	v_add3_u32 v8, v36, v8, s5
	s_waitcnt lgkmcnt(0)
	v_bfe_u32 v10, v38, 16, 1
	v_lshrrev_b32_e32 v8, 16, v8
	v_add3_u32 v10, v38, v10, s5
	v_and_or_b32 v31, v10, s35, v8
	v_add_u32_e32 v8, s15, v16
	v_mad_u64_u32 v[40:41], s[10:11], v8, s14, 0
	v_ashrrev_i32_e32 v10, 31, v8
	v_mov_b32_e32 v8, v41
	v_mad_u64_u32 v[42:43], s[10:11], v10, s14, v[8:9]
	v_mov_b32_e32 v41, v42
	v_lshl_add_u64 v[40:41], v[40:41], 1, s[8:9]
	v_bfe_u32 v8, v45, 16, 1
	v_lshl_add_u64 v[40:41], v[40:41], 0, s[0:1]
	v_add3_u32 v8, v45, v8, s5
	v_bfe_u32 v10, v47, 16, 1
	v_lshl_add_u64 v[40:41], v[40:41], 0, v[4:5]
	v_lshrrev_b32_e32 v8, 16, v8
	v_add3_u32 v10, v47, v10, s5
	global_store_dwordx4 v[40:41], v[28:31], off
	s_nop 1
	v_and_or_b32 v28, v10, s35, v8
	v_bfe_u32 v8, v9, 16, 1
	v_add3_u32 v8, v9, v8, s5
	v_bfe_u32 v9, v15, 16, 1
	v_lshrrev_b32_e32 v8, 16, v8
	v_add3_u32 v9, v15, v9, s5
	v_and_or_b32 v29, v9, s35, v8
	v_bfe_u32 v8, v33, 16, 1
	v_add3_u32 v8, v33, v8, s5
	v_bfe_u32 v9, v35, 16, 1
	v_lshrrev_b32_e32 v8, 16, v8
	v_add3_u32 v9, v35, v9, s5
	v_and_or_b32 v30, v9, s35, v8
	v_bfe_u32 v8, v37, 16, 1
	v_add3_u32 v8, v37, v8, s5
	v_bfe_u32 v9, v39, 16, 1
	v_lshrrev_b32_e32 v8, 16, v8
	v_add3_u32 v9, v39, v9, s5
	v_and_or_b32 v31, v9, s35, v8
	v_add_u32_e32 v8, s15, v17
	v_ashrrev_i32_e32 v12, 31, v8
	v_mad_u64_u32 v[8:9], s[10:11], v8, s14, 0
	v_mov_b32_e32 v10, v9
	v_mad_u64_u32 v[14:15], s[10:11], v12, s14, v[10:11]
	v_mov_b32_e32 v9, v14
	v_lshl_add_u64 v[8:9], v[8:9], 1, s[8:9]
	v_lshl_add_u64 v[8:9], v[8:9], 0, s[0:1]
	v_lshl_add_u64 v[8:9], v[8:9], 0, v[4:5]
	global_store_dwordx4 v[8:9], v[28:31], off
	s_waitcnt lgkmcnt(0)
	s_cbranch_scc1 .LBB0_82

; #define LAS __attribute__((address_space(3)))
; __device__ __forceinline__ void transpose_item(const Job& jb, LAS float* scr, int item, int lane) {
;     const int K = jb.K, N = jb.N; const int nblk = N / 32, kb = item / nblk, nb = item % nblk, k0 = 64 * kb, n0 = 32 * nb;
;     int r0 = n0; if (jb.mode) r0 = 256 * (n0 / 128) + (n0 % 128) + (jb.mode == 2 ? 128 : 0);
; #pragma unroll
;     for (int i = 0; i < 8; ++i) { const int kk = 8 * i + (lane >> 3), c4 = 4 * (lane & 7); const float g = jb.gain ? jb.gain[k0 + kk] : 1.0f;
;         const f32x4 v = *(const f32x4*)(jb.src + (size_t)(k0 + kk) * N + n0 + c4); LAS float* d = scr + kk * 33 + c4;
;         d[0] = v.x * g; d[1] = v.y * g; d[2] = v.z * g; d[3] = v.w * g; }
.LBB0_63:
	s_lshl_b32 s12, s12, 6
	v_or_b32_e32 v14, s12, v2
	v_ashrrev_i32_e32 v15, 31, v14
	s_ashr_i32 s13, s12, 31
	s_mul_i32 s3, s13, s74
	s_cmp_eq_u64 s[10:11], 0
	s_cbranch_scc1 .Lpro_nogain
	v_lshl_add_u64 v[8:9], v[14:15], 2, s[10:11]
	global_load_dword v80, v[8:9], off
	global_load_dword v82, v[8:9], off offset:32
	global_load_dword v84, v[8:9], off offset:64
	global_load_dword v86, v[8:9], off offset:96
	global_load_dword v88, v[8:9], off offset:128
	global_load_dword v90, v[8:9], off offset:160
	global_load_dword v92, v[8:9], off offset:192
	global_load_dword v94, v[8:9], off offset:224
	s_branch .Lpro_rows
.Lpro_nogain:
	v_mov_b32_e32 v80, 1.0
	v_mov_b32_e32 v82, 1.0
	v_mov_b32_e32 v84, 1.0
	v_mov_b32_e32 v86, 1.0
	v_mov_b32_e32 v88, 1.0
	v_mov_b32_e32 v90, 1.0
	v_mov_b32_e32 v92, 1.0
	v_mov_b32_e32 v94, 1.0
.Lpro_rows:
	s_ashr_i32 s89, s88, 31
	s_lshl_b64 s[78:79], s[88:89], 2
	s_add_u32 s0, s0, s78
	s_addc_u32 s1, s1, s79
	v_lshl_add_u64 v[8:9], s[0:1], 0, v[6:7]
	v_or_b32_e32 v12, s12, v2
	v_mad_u64_u32 v[14:15], s[78:79], v12, s74, 0
	v_add_u32_e32 v15, s3, v15
	v_lshl_add_u64 v[14:15], v[14:15], 2, v[8:9]
	global_load_dwordx4 v[96:99], v[14:15], off
	v_or_b32_e32 v12, s12, v13
	v_mad_u64_u32 v[14:15], s[78:79], v12, s74, 0
	v_add_u32_e32 v15, s3, v15
	v_lshl_add_u64 v[14:15], v[14:15], 2, v[8:9]
	global_load_dwordx4 v[100:103], v[14:15], off
	v_or_b32_e32 v12, s12, v16
	v_mad_u64_u32 v[14:15], s[78:79], v12, s74, 0
	v_add_u32_e32 v15, s3, v15
	v_lshl_add_u64 v[14:15], v[14:15], 2, v[8:9]
	global_load_dwordx4 v[104:107], v[14:15], off
	v_or_b32_e32 v12, s12, v17
	v_mad_u64_u32 v[14:15], s[78:79], v12, s74, 0
	v_add_u32_e32 v15, s3, v15
	v_lshl_add_u64 v[14:15], v[14:15], 2, v[8:9]
	global_load_dwordx4 v[108:111], v[14:15], off
	v_or_b32_e32 v12, s12, v18
	v_mad_u64_u32 v[14:15], s[78:79], v12, s74, 0
	v_add_u32_e32 v15, s3, v15
	v_lshl_add_u64 v[14:15], v[14:15], 2, v[8:9]
	global_load_dwordx4 v[112:115], v[14:15], off
	v_or_b32_e32 v12, s12, v19
	v_mad_u64_u32 v[14:15], s[78:79], v12, s74, 0
	v_add_u32_e32 v15, s3, v15
	v_lshl_add_u64 v[14:15], v[14:15], 2, v[8:9]
	global_load_dwordx4 v[116:119], v[14:15], off
	v_or_b32_e32 v12, s12, v20
	v_mad_u64_u32 v[14:15], s[78:79], v12, s74, 0
	v_add_u32_e32 v15, s3, v15
	v_lshl_add_u64 v[14:15], v[14:15], 2, v[8:9]
	global_load_dwordx4 v[120:123], v[14:15], off
	v_or_b32_e32 v12, s12, v21
	v_mad_u64_u32 v[14:15], s[78:79], v12, s74, 0
	v_add_u32_e32 v15, s3, v15
	v_lshl_add_u64 v[14:15], v[14:15], 2, v[8:9]
	global_load_dwordx4 v[124:127], v[14:15], off
	v_add_u32_e32 v32, 0xc60, v23
	v_add_u32_e32 v33, 0xc68, v23
	v_add_u32_e32 v34, 0x1080, v23
	v_add_u32_e32 v35, 0x1088, v23
	v_add_u32_e32 v36, 0x14a0, v23
	v_add_u32_e32 v37, 0x14a8, v23
	v_add_u32_e32 v38, 0x18c0, v23
	v_add_u32_e32 v39, 0x18c8, v23
	v_add_u32_e32 v40, 0x1ce0, v23
	v_add_u32_e32 v41, 0x1ce8, v23
	s_waitcnt vmcnt(7)
	v_pk_mul_f32 v[96:97], v[80:81], v[96:97] op_sel_hi:[0,1]
	v_pk_mul_f32 v[98:99], v[80:81], v[98:99] op_sel_hi:[0,1]
	ds_write2_b32 v23, v96, v97 offset1:1
	ds_write2_b32 v23, v98, v99 offset0:2 offset1:3
	s_waitcnt vmcnt(6)
	v_pk_mul_f32 v[100:101], v[82:83], v[100:101] op_sel_hi:[0,1]
	v_pk_mul_f32 v[102:103], v[82:83], v[102:103] op_sel_hi:[0,1]
	ds_write2_b32 v24, v100, v101 offset1:1
	ds_write2_b32 v25, v102, v103 offset1:1
	s_waitcnt vmcnt(5)
	v_pk_mul_f32 v[104:105], v[84:85], v[104:105] op_sel_hi:[0,1]
	v_pk_mul_f32 v[106:107], v[84:85], v[106:107] op_sel_hi:[0,1]
	ds_write2_b32 v26, v104, v105 offset1:1
	ds_write2_b32 v27, v106, v107 offset1:1
	s_waitcnt vmcnt(4)
	v_pk_mul_f32 v[108:109], v[86:87], v[108:109] op_sel_hi:[0,1]
	v_pk_mul_f32 v[110:111], v[86:87], v[110:111] op_sel_hi:[0,1]
	ds_write2_b32 v32, v108, v109 offset1:1
	ds_write2_b32 v33, v110, v111 offset1:1
	s_waitcnt vmcnt(3)
	v_pk_mul_f32 v[112:113], v[88:89], v[112:113] op_sel_hi:[0,1]
	v_pk_mul_f32 v[114:115], v[88:89], v[114:115] op_sel_hi:[0,1]
	ds_write2_b32 v34, v112, v113 offset1:1
	ds_write2_b32 v35, v114, v115 offset1:1
	s_waitcnt vmcnt(2)
	v_pk_mul_f32 v[116:117], v[90:91], v[116:117] op_sel_hi:[0,1]
	v_pk_mul_f32 v[118:119], v[90:91], v[118:119] op_sel_hi:[0,1]
	ds_write2_b32 v36, v116, v117 offset1:1
	ds_write2_b32 v37, v118, v119 offset1:1
	s_waitcnt vmcnt(1)
	v_pk_mul_f32 v[120:121], v[92:93], v[120:121] op_sel_hi:[0,1]
	v_pk_mul_f32 v[122:123], v[92:93], v[122:123] op_sel_hi:[0,1]
	ds_write2_b32 v38, v120, v121 offset1:1
	ds_write2_b32 v39, v122, v123 offset1:1
	s_waitcnt vmcnt(0)
	v_pk_mul_f32 v[124:125], v[94:95], v[124:125] op_sel_hi:[0,1]
	v_pk_mul_f32 v[126:127], v[94:95], v[126:127] op_sel_hi:[0,1]
	ds_write2_b32 v40, v124, v125 offset1:1
	ds_write2_b32 v41, v126, v127 offset1:1
	s_branch .LBB0_7

; template <int l> __device__ __forceinline__ void layer_body(const Args& args, LAS unsigned char* lds, const XcdBarrier& bar) {
;     ...
;                             st0 = st0 - m_run; st1 = st1 - m_run;
; #pragma unroll
;                             for (int i = 0; i < 16; ++i) { st0[i] = __builtin_amdgcn_exp2f(st0[i]); st1[i] = __builtin_amdgcn_exp2f(st1[i]); }
;                             { float ps = (((st0[0] + st0[1]) + (st0[2] + st0[3])) + ((st0[4] + st0[5]) + (st0[6] + st0[7]))) + (((st0[8] + st0[9]) + (st0[10] + st0[11])) + ((st0[12] + st0[13]) + (st0[14] + st0[15])));
;                               ps += (((st1[0] + st1[1]) + (st1[2] + st1[3])) + ((st1[4] + st1[5]) + (st1[6] + st1[7]))) + (((st1[8] + st1[9]) + (st1[10] + st1[11])) + ((st1[12] + st1[13]) + (st1[14] + st1[15])));
;                               { auto rr_ = __builtin_amdgcn_permlane32_swap(__float_as_uint(ps), __float_as_uint(ps), false, false); ps = __uint_as_float(rr_[0]) + __uint_as_float(rr_[1]); }
;                               l_run += ps; }
;                             { v4u p0, p1; p0.x = cvtpk(st0[0], st0[1]); p0.y = cvtpk(st0[2], st0[3]); p0.z = cvtpk(st0[4], st0[5]); p0.w = cvtpk(st0[6], st0[7]);
;                               p1.x = cvtpk(st0[8], st0[9]); p1.y = cvtpk(st0[10], st0[11]); p1.z = cvtpk(st0[12], st0[13]); p1.w = cvtpk(st0[14], st0[15]);
;                               const bf16x8 pf0 = __builtin_bit_cast(bf16x8, p0), pf1 = __builtin_bit_cast(bf16x8, p1);
; #pragma unroll
;                               for (int dg = 0; dg < 4; ++dg) { o[dg] = MFMA32(*(const LAS bf16x8*)(vl + dg * 256), pf0, o[dg]); o[dg] = MFMA32(*(const LAS bf16x8*)(vl + 2048 + dg * 256), pf1, o[dg]); } }
;                             { v4u p0, p1; p0.x = cvtpk(st1[0], st1[1]); p0.y = cvtpk(st1[2], st1[3]); p0.z = cvtpk(st1[4], st1[5]); p0.w = cvtpk(st1[6], st1[7]);
;                               p1.x = cvtpk(st1[8], st1[9]); p1.y = cvtpk(st1[10], st1[11]); p1.z = cvtpk(st1[12], st1[13]); p1.w = cvtpk(st1[14], st1[15]);
;                               const bf16x8 pf0 = __builtin_bit_cast(bf16x8, p0), pf1 = __builtin_bit_cast(bf16x8, p1);
; #pragma unroll
;                               for (int dg = 0; dg < 4; ++dg) { o[dg] = MFMA32(*(const LAS bf16x8*)(vl + 4096 + dg * 256), pf0, o[dg]); o[dg] = MFMA32(*(const LAS bf16x8*)(vl + 4096 + 2048 + dg * 256), pf1, o[dg]); } }
.LBB0_1508:
	v_sub_f32_e32 v80, v111, v193
	v_sub_f32_e32 v81, v110, v193
	v_sub_f32_e32 v82, v105, v193
	v_sub_f32_e32 v83, v104, v193
	v_add_u32_e32 v202, s76, v179
	v_exp_f32_e32 v199, v83
	v_exp_f32_e32 v201, v82
	v_exp_f32_e32 v207, v81
	v_exp_f32_e32 v209, v80
	v_sub_f32_e32 v86, v101, v193
	v_sub_f32_e32 v87, v100, v193
	v_sub_f32_e32 v88, v103, v193
	v_sub_f32_e32 v89, v102, v193
	v_sub_f32_e32 v90, v99, v193
	v_sub_f32_e32 v91, v98, v193
	v_sub_f32_e32 v92, v97, v193
	v_sub_f32_e32 v93, v96, v193
	v_sub_f32_e32 v1, v109, v193
	v_sub_f32_e32 v84, v107, v193
	v_exp_f32_e32 v101, v93
	v_exp_f32_e32 v103, v92
	v_exp_f32_e32 v105, v91
	v_exp_f32_e32 v107, v90
	v_exp_f32_e32 v109, v89
	v_exp_f32_e32 v111, v88
	v_exp_f32_e32 v195, v87
	v_exp_f32_e32 v197, v86
	v_sub_f32_e32 v85, v106, v193
	v_exp_f32_e32 v211, v85
	v_exp_f32_e32 v213, v84
	v_cvt_pk_bf16_f32 v84, v101, v103
	v_cvt_pk_bf16_f32 v85, v105, v107
	v_cvt_pk_bf16_f32 v86, v109, v111
	v_cvt_pk_bf16_f32 v87, v195, v197
	v_sub_f32_e32 v108, v108, v193
	s_waitcnt lgkmcnt(7)
	v_mfma_f32_32x32x16_bf16 v[64:79], v[218:221], v[84:87], v[64:79]
	ds_read_b128 v[218:221], v202 offset:40960
	v_exp_f32_e32 v215, v108
	v_exp_f32_e32 v217, v1
	v_cvt_pk_bf16_f32 v80, v199, v201
	v_cvt_pk_bf16_f32 v81, v207, v209
	v_cvt_pk_bf16_f32 v82, v211, v213
	v_cvt_pk_bf16_f32 v83, v215, v217
	s_waitcnt lgkmcnt(7)
	v_mfma_f32_32x32x16_bf16 v[48:63], v[222:225], v[84:87], v[48:63]
	ds_read_b128 v[222:225], v202 offset:41472
	v_sub_f32_e32 v92, v174, v193
	v_sub_f32_e32 v93, v15, v193
	v_sub_f32_e32 v94, v14, v193
	v_sub_f32_e32 v95, v13, v193
	v_sub_f32_e32 v174, v8, v193
	v_sub_f32_e32 v7, v7, v193
	v_sub_f32_e32 v6, v6, v193
	s_waitcnt lgkmcnt(7)
	v_mfma_f32_32x32x16_bf16 v[64:79], v[226:229], v[80:83], v[64:79]
	ds_read_b128 v[226:229], v202 offset:45056
	v_exp_f32_e32 v108, v6
	v_exp_f32_e32 v110, v7
	v_exp_f32_e32 v194, v174
	v_sub_f32_e32 v1, v175, v193
	v_exp_f32_e32 v208, v95
	v_exp_f32_e32 v210, v94
	s_waitcnt lgkmcnt(7)
	v_mfma_f32_32x32x16_bf16 v[48:63], v[230:233], v[80:83], v[48:63]
	ds_read_b128 v[230:233], v202 offset:45568
	v_sub_f32_e32 v96, v12, v193
	v_sub_f32_e32 v97, v11, v193
	v_sub_f32_e32 v98, v10, v193
	v_sub_f32_e32 v99, v9, v193
	v_exp_f32_e32 v196, v99
	v_exp_f32_e32 v198, v98
	s_waitcnt lgkmcnt(7)
	v_mfma_f32_32x32x16_bf16 v[32:47], v[234:237], v[84:87], v[32:47]
	ds_read_b128 v[234:237], v202 offset:41984
	v_sub_f32_e32 v88, v5, v193
	v_sub_f32_e32 v89, v4, v193
	v_sub_f32_e32 v90, v3, v193
	v_sub_f32_e32 v91, v2, v193
	v_exp_f32_e32 v100, v91
	v_exp_f32_e32 v102, v90
	s_waitcnt lgkmcnt(7)
	v_mfma_f32_32x32x16_bf16 v[16:31], v[238:241], v[84:87], v[16:31]
	ds_read_b128 v[238:241], v202 offset:42496
	v_exp_f32_e32 v104, v89
	v_exp_f32_e32 v106, v88
	v_exp_f32_e32 v200, v97
	v_exp_f32_e32 v206, v96
	v_exp_f32_e32 v212, v93
	v_exp_f32_e32 v214, v92
	v_exp_f32_e32 v216, v1
	s_waitcnt lgkmcnt(7)
	v_mfma_f32_32x32x16_bf16 v[32:47], v[242:245], v[80:83], v[32:47]
	ds_read_b128 v[242:245], v202 offset:46080
	s_waitcnt lgkmcnt(7)
	v_mfma_f32_32x32x16_bf16 v[16:31], v[246:249], v[80:83], v[16:31]
	ds_read_b128 v[246:249], v202 offset:46592
	v_cvt_pk_bf16_f32 v2, v100, v102
	v_cvt_pk_bf16_f32 v3, v104, v106
	v_cvt_pk_bf16_f32 v4, v108, v110
	v_cvt_pk_bf16_f32 v5, v194, v196
	s_waitcnt lgkmcnt(7)
	s_nop 0
	v_mfma_f32_32x32x16_bf16 v[64:79], v[218:221], v[2:5], v[64:79]
	v_cvt_pk_bf16_f32 v6, v198, v200
	v_cvt_pk_bf16_f32 v7, v206, v208
	v_cvt_pk_bf16_f32 v8, v210, v212
	v_cvt_pk_bf16_f32 v9, v214, v216
	s_waitcnt lgkmcnt(6)
	v_mfma_f32_32x32x16_bf16 v[48:63], v[222:225], v[2:5], v[48:63]
	s_nop 0
	s_waitcnt lgkmcnt(5)
	v_mfma_f32_32x32x16_bf16 v[64:79], v[226:229], v[6:9], v[64:79]
	s_waitcnt lgkmcnt(4)
	v_mfma_f32_32x32x16_bf16 v[48:63], v[230:233], v[6:9], v[48:63]
	s_waitcnt lgkmcnt(3)
	v_mfma_f32_32x32x16_bf16 v[32:47], v[234:237], v[2:5], v[32:47]
	v_add_f32_e64 v10, v100, v102
	v_add_f32_e64 v11, v101, v103
	v_add_f32_e64 v12, v104, v106
	v_add_f32_e64 v13, v105, v107
	v_add_f32_e64 v14, v10, v12
	v_add_f32_e64 v15, v11, v13
	v_pk_add_f32 v[10:11], v[108:109], v[110:111]
	v_pk_add_f32 v[12:13], v[194:195], v[196:197]
	s_nop 0
	v_pk_add_f32 v[88:89], v[10:11], v[12:13]
	s_waitcnt lgkmcnt(2)
	v_mfma_f32_32x32x16_bf16 v[16:31], v[238:241], v[2:5], v[16:31]
	v_add_f32_e64 v14, v14, v88
	v_add_f32_e64 v15, v15, v89
	v_add_f32_e64 v88, v214, v216
	v_add_f32_e64 v89, v215, v217
	s_waitcnt lgkmcnt(1)
	v_mfma_f32_32x32x16_bf16 v[32:47], v[242:245], v[6:9], v[32:47]
	v_add_f32_e64 v80, v198, v200
	v_add_f32_e64 v81, v199, v201
	v_add_f32_e64 v82, v206, v208
	v_add_f32_e64 v83, v207, v209
	v_add_f32_e64 v80, v80, v82
	v_add_f32_e64 v81, v81, v83
	v_pk_add_f32 v[82:83], v[210:211], v[212:213]
	s_nop 0
	v_pk_add_f32 v[82:83], v[82:83], v[88:89]
	s_waitcnt lgkmcnt(0)
	v_mfma_f32_32x32x16_bf16 v[16:31], v[246:249], v[6:9], v[16:31]
	v_add_f32_e64 v2, v80, v82
	v_add_f32_e64 v3, v81, v83
	v_add_f32_e64 v2, v14, v2
	v_add_f32_e64 v3, v15, v3
	v_pk_add_f32 v[2:3], v[2:3], v[2:3] op_sel:[0,1] op_sel_hi:[1,0]
	s_nop 0
	v_mov_b32_e32 v1, v2
	s_nop 1
	v_permlane32_swap_b32_e32 v2, v1
	v_add_f32_e32 v1, v2, v1
	v_add_f32_e32 v190, v190, v1

; #define LAS __attribute__((address_space(3)))
; #define MFMA32(a, b, c) __builtin_amdgcn_mfma_f32_32x32x16_bf16((a), (b), (c), 0, 0, 0)
; template <int l> __device__ __forceinline__ void layer_body(const Args& args, LAS unsigned char* lds, const XcdBarrier& bar) {
;     ...
;                             const LAS bf16* kl = (const LAS bf16*)(lds + (u & 1) * 16384) + (hh * 32 + pr) * 8; const LAS bf16* vl = (const LAS bf16*)(lds + 32768 + (u & 1) * 16384) + (hh * 128 + r) * 8;
;                             f32x16 st0, st1;
;                             { bf16x8 kfa[8], kfb[8];
; #pragma unroll
;                               for (int s = 0; s < 8; ++s) { kfa[s] = *(const LAS bf16x8*)(kl + s * 512); kfb[s] = *(const LAS bf16x8*)(kl + 4096 + s * 512); }
; #pragma unroll
;                               for (int i = 0; i < 16; ++i) { st0[i] = 0.f; st1[i] = 0.f; }
; #pragma unroll
;                               for (int s = 0; s < 8; ++s) { st0 = MFMA32(kfa[s], qf[s], st0); st1 = MFMA32(kfb[s], qf[s], st1); } }
;     ...
;                               for (int dg = 0; dg < 4; ++dg) { o[dg] = MFMA32(*(const LAS bf16x8*)(vl + dg * 256), pf0, o[dg]); o[dg] = MFMA32(*(const LAS bf16x8*)(vl + 2048 + dg * 256), pf1, o[dg]); } }
.LBB0_1512:
	s_cmp_gt_i32 s63, s61
	s_cbranch_scc1 .LBB0_1509
	s_and_b32 s76, s48, 0x4000
	v_add_u32_e32 v1, s76, v145
	ds_read_b128 v[218:221], v1
	ds_read_b128 v[222:225], v1 offset:8192
	ds_read_b128 v[226:229], v1 offset:1024
	ds_read_b128 v[230:233], v1 offset:9216
	ds_read_b128 v[234:237], v1 offset:2048
	ds_read_b128 v[238:241], v1 offset:10240
	ds_read_b128 v[242:245], v1 offset:3072
	ds_read_b128 v[246:249], v1 offset:11264
	s_lshr_b32 s77, s75, 2
	s_cmp_lt_i32 s63, s61
	s_mov_b64 s[10:11], -1
	v_add_u32_e32 v202, s76, v179
	s_waitcnt lgkmcnt(7)
	v_mfma_f32_32x32x16_bf16 v[80:95], v[218:221], v[112:115], 0
	ds_read_b128 v[218:221], v1 offset:4096
	s_waitcnt lgkmcnt(7)
	v_mfma_f32_32x32x16_bf16 v[96:111], v[222:225], v[112:115], 0
	ds_read_b128 v[222:225], v1 offset:12288
	s_waitcnt lgkmcnt(7)
	v_mfma_f32_32x32x16_bf16 v[80:95], v[226:229], v[116:119], v[80:95]
	ds_read_b128 v[226:229], v1 offset:5120
	s_waitcnt lgkmcnt(7)
	v_mfma_f32_32x32x16_bf16 v[96:111], v[230:233], v[116:119], v[96:111]
	ds_read_b128 v[230:233], v1 offset:13312
	s_waitcnt lgkmcnt(7)
	v_mfma_f32_32x32x16_bf16 v[80:95], v[234:237], v[120:123], v[80:95]
	ds_read_b128 v[234:237], v1 offset:6144
	s_waitcnt lgkmcnt(7)
	v_mfma_f32_32x32x16_bf16 v[96:111], v[238:241], v[120:123], v[96:111]
	ds_read_b128 v[238:241], v1 offset:14336
	s_waitcnt lgkmcnt(7)
	v_mfma_f32_32x32x16_bf16 v[80:95], v[242:245], v[124:127], v[80:95]
	ds_read_b128 v[242:245], v1 offset:7168
	s_waitcnt lgkmcnt(7)
	v_mfma_f32_32x32x16_bf16 v[96:111], v[246:249], v[124:127], v[96:111]
	ds_read_b128 v[246:249], v1 offset:15360
	s_waitcnt lgkmcnt(7)
	v_mfma_f32_32x32x16_bf16 v[80:95], v[218:221], v[128:131], v[80:95]
	s_waitcnt lgkmcnt(6)
	v_mfma_f32_32x32x16_bf16 v[96:111], v[222:225], v[128:131], v[96:111]
	s_waitcnt lgkmcnt(5)
	v_mfma_f32_32x32x16_bf16 v[80:95], v[226:229], v[132:135], v[80:95]
	s_waitcnt lgkmcnt(4)
	v_mfma_f32_32x32x16_bf16 v[96:111], v[230:233], v[132:135], v[96:111]
	s_waitcnt lgkmcnt(3)
	v_mfma_f32_32x32x16_bf16 v[80:95], v[234:237], v[136:139], v[80:95]
	s_waitcnt lgkmcnt(2)
	v_mfma_f32_32x32x16_bf16 v[96:111], v[238:241], v[136:139], v[96:111]
	s_waitcnt lgkmcnt(1)
	v_mfma_f32_32x32x16_bf16 v[80:95], v[242:245], v[140:143], v[80:95]
	s_waitcnt lgkmcnt(0)
	v_mfma_f32_32x32x16_bf16 v[96:111], v[246:249], v[140:143], v[96:111]
	ds_read_b128 v[218:221], v202 offset:32768
	ds_read_b128 v[222:225], v202 offset:33280
	ds_read_b128 v[226:229], v202 offset:36864
	ds_read_b128 v[230:233], v202 offset:37376
	ds_read_b128 v[234:237], v202 offset:33792
	ds_read_b128 v[238:241], v202 offset:34304
	ds_read_b128 v[242:245], v202 offset:37888
	ds_read_b128 v[246:249], v202 offset:38400
	s_cbranch_scc1 .LBB0_1515
	s_lshl_b32 s10, 1, s77
	v_and_b32_e32 v1, s10, v189
	s_mov_b64 s[10:11], 0
